# grid barrier: XCD leader's invalidate moved to right after its L2 writeback (all local workgroups already arrived), off the cross-XCD-release -> local-release path; on top of arrival-time invalidate f
# baseline (speedup 1.0000x reference)
.Lgs0_b187:
	s_andn2_saveexec_b64 s[18:19], s[18:19]
	s_cbranch_execz .Lgs0_end
	s_mov_b64 s[18:19], exec
	buffer_wbl2 sc1
	s_waitcnt lgkmcnt(0)
	s_waitcnt vmcnt(0)
	buffer_inv sc1
	v_mbcnt_lo_u32_b32 v1, s18, 0
	v_mbcnt_hi_u32_b32 v1, s19, v1
	v_cmp_eq_u32_e32 vcc, 0, v1
	s_and_saveexec_b64 s[22:23], vcc
	s_cbranch_execz .Lgs0_b190
	s_bcnt1_i32_b64 s18, s[18:19]
	v_mov_b32_e32 v2, s18
	v_readlane_b32 s18, v255, 2
	v_readlane_b32 s19, v255, 3
	s_nop 4
	global_atomic_add v2, v17, v2, s[18:19] sc0

.Lgs0_b204:
	s_or_b64 exec, exec, s[18:19]
	s_mov_b64 s[18:19], exec
	v_mbcnt_lo_u32_b32 v0, s18, 0
	v_mbcnt_hi_u32_b32 v0, s19, v0
	v_cmp_eq_u32_e32 vcc, 0, v0
	s_waitcnt vmcnt(0)
	s_nop 0
	s_and_saveexec_b64 s[22:23], vcc
	s_cbranch_execz .Lgs0_b206
	s_bcnt1_i32_b64 s18, s[18:19]
	v_mov_b32_e32 v0, s18
	v_readlane_b32 s18, v255, 0
	v_readlane_b32 s19, v255, 1
	s_nop 4
	global_atomic_add v17, v0, s[18:19]

.LBB0_688:
	s_andn2_saveexec_b64 s[14:15], s[14:15]
	s_cbranch_execz .LBB0_708
	s_mov_b64 s[14:15], exec
	buffer_wbl2 sc1
	s_waitcnt lgkmcnt(0)
	s_waitcnt vmcnt(0)
	buffer_inv sc1
	v_mbcnt_lo_u32_b32 v1, s14, 0
	v_mbcnt_hi_u32_b32 v1, s15, v1
	v_cmp_eq_u32_e32 vcc, 0, v1
	s_and_saveexec_b64 s[18:19], vcc
	s_cbranch_execz .LBB0_691
	s_bcnt1_i32_b64 s14, s[14:15]
	v_mov_b32_e32 v2, s14
	v_readlane_b32 s14, v255, 2
	v_readlane_b32 s15, v255, 3
	s_nop 4
	global_atomic_add v2, v17, v2, s[14:15] sc0

.LBB0_705:
	s_or_b64 exec, exec, s[14:15]
	s_mov_b64 s[14:15], exec
	v_mbcnt_lo_u32_b32 v0, s14, 0
	v_mbcnt_hi_u32_b32 v0, s15, v0
	v_cmp_eq_u32_e32 vcc, 0, v0
	s_waitcnt vmcnt(0)
	s_nop 0
	s_and_saveexec_b64 s[18:19], vcc
	s_cbranch_execz .LBB0_707
	s_bcnt1_i32_b64 s14, s[14:15]
	v_mov_b32_e32 v0, s14
	v_readlane_b32 s14, v255, 0
	v_readlane_b32 s15, v255, 1
	s_nop 4
	global_atomic_add v17, v0, s[14:15]

.LBB0_1034:
	s_mov_b64 s[14:15], exec
	buffer_wbl2 sc1
	s_waitcnt lgkmcnt(0)
	s_waitcnt vmcnt(0)
	buffer_inv sc1
	v_mbcnt_lo_u32_b32 v1, s14, 0
	v_mbcnt_hi_u32_b32 v1, s15, v1
	v_cmp_eq_u32_e32 vcc, 0, v1
	s_and_saveexec_b64 s[18:19], vcc
	s_cbranch_execz .LBB0_1036
	s_bcnt1_i32_b64 s14, s[14:15]
	v_mov_b32_e32 v2, s14
	v_readlane_b32 s14, v255, 2
	v_readlane_b32 s15, v255, 3
	s_nop 4
	global_atomic_add v2, v17, v2, s[14:15] sc0

.LBB0_1050:
	s_or_b64 exec, exec, s[14:15]
	s_mov_b64 s[14:15], exec
	v_mbcnt_lo_u32_b32 v0, s14, 0
	v_mbcnt_hi_u32_b32 v0, s15, v0
	v_cmp_eq_u32_e32 vcc, 0, v0
	s_waitcnt vmcnt(0)
	s_nop 0
	s_and_saveexec_b64 s[18:19], vcc
	s_cbranch_execnz .LBB0_1051
	s_getpc_b64 s[98:99]
